# grid barrier arrival inside an XCD via per-workgroup plain-store flags polled by a fixed leader (no returning device-scope atomic after the first barrier)
# speedup vs baseline: 1.0064x; 1.0003x over previous
.LBB0_1111:
	s_mov_b32 s20, 0
	v_writelane_b32 v255, s20, 33
	v_readlane_b32 s8, v253, 24
	v_readlane_b32 s9, v253, 25
	v_cmp_ne_u32_e32 vcc, 0, v0
	s_nop 0
	v_cndmask_b32_e64 v17, 0, v0, s[8:9]
	v_readlane_b32 s8, v253, 22
	v_readlane_b32 s9, v253, 23
	v_cndmask_b32_e64 v0, 0, 1, vcc
	v_cmp_ne_u32_e32 vcc, 0, v2
	v_cndmask_b32_e64 v17, v17, v2, s[8:9]
	v_readlane_b32 s8, v253, 20
	v_readlane_b32 s9, v253, 21
	v_addc_co_u32_e32 v0, vcc, 0, v0, vcc
	s_nop 0
	v_cndmask_b32_e64 v17, v17, v3, s[8:9]
	v_readlane_b32 s8, v253, 18
	v_readlane_b32 s9, v253, 19
	v_cmp_ne_u32_e32 vcc, 0, v3
	s_nop 0
	v_cndmask_b32_e64 v17, v17, v4, s[8:9]
	v_readlane_b32 s8, v253, 16
	v_readlane_b32 s9, v253, 17
	v_cndmask_b32_e64 v2, 0, 1, vcc
	v_cmp_ne_u32_e32 vcc, 0, v4
	v_cndmask_b32_e64 v17, v17, v5, s[8:9]
	v_readlane_b32 s8, v253, 14
	v_readlane_b32 s9, v253, 15
	v_addc_co_u32_e32 v0, vcc, v0, v2, vcc
	s_nop 0
	v_cndmask_b32_e64 v17, v17, v6, s[8:9]
	v_readlane_b32 s8, v253, 12
	v_readlane_b32 s9, v253, 13
	v_cmp_ne_u32_e32 vcc, 0, v5
	s_nop 0
	v_cndmask_b32_e64 v17, v17, v7, s[8:9]
	v_readlane_b32 s8, v253, 10
	v_readlane_b32 s9, v253, 11
	v_cndmask_b32_e64 v2, 0, 1, vcc
	v_cmp_ne_u32_e32 vcc, 0, v6
	v_cndmask_b32_e64 v17, v17, v8, s[8:9]
	v_readlane_b32 s8, v253, 8
	v_readlane_b32 s9, v253, 9
	v_addc_co_u32_e32 v0, vcc, v0, v2, vcc
	s_nop 0
	v_cndmask_b32_e64 v17, v17, v9, s[8:9]
	v_readlane_b32 s8, v253, 6
	v_cmp_ne_u32_e32 vcc, 0, v7
	v_readlane_b32 s9, v253, 7
	s_nop 0
	v_cndmask_b32_e64 v2, 0, 1, vcc
	v_cmp_ne_u32_e32 vcc, 0, v8
	v_cndmask_b32_e64 v17, v17, v10, s[8:9]
	v_readlane_b32 s8, v253, 4
	v_addc_co_u32_e32 v0, vcc, v0, v2, vcc
	v_readlane_b32 s9, v253, 5
	v_cmp_ne_u32_e32 vcc, 0, v9
	s_nop 0
	v_cndmask_b32_e64 v17, v17, v11, s[8:9]
	v_readlane_b32 s8, v253, 2
	v_cndmask_b32_e64 v2, 0, 1, vcc
	v_cmp_ne_u32_e32 vcc, 0, v10
	v_readlane_b32 s9, v253, 3
	s_nop 0
	v_addc_co_u32_e32 v0, vcc, v0, v2, vcc
	v_cndmask_b32_e64 v17, v17, v12, s[8:9]
	v_readlane_b32 s8, v253, 0
	v_cmp_ne_u32_e32 vcc, 0, v11
	v_readlane_b32 s9, v253, 1
	s_nop 0
	v_cndmask_b32_e64 v2, 0, 1, vcc
	v_cmp_ne_u32_e32 vcc, 0, v12
	v_cndmask_b32_e64 v17, v17, v13, s[8:9]
	v_readlane_b32 s8, v252, 62
	v_addc_co_u32_e32 v0, vcc, v0, v2, vcc
	v_readlane_b32 s9, v252, 63
	v_cmp_ne_u32_e32 vcc, 0, v13
	s_nop 0
	v_cndmask_b32_e64 v17, v17, v14, s[8:9]
	v_readlane_b32 s8, v252, 60
	v_cndmask_b32_e64 v2, 0, 1, vcc
	v_cmp_ne_u32_e32 vcc, 0, v14
	v_readlane_b32 s9, v252, 61
	s_nop 0
	v_addc_co_u32_e32 v0, vcc, v0, v2, vcc
	v_cndmask_b32_e64 v17, v17, v15, s[8:9]
	v_readlane_b32 s8, v252, 58
	v_cmp_ne_u32_e32 vcc, 0, v15
	v_readlane_b32 s9, v252, 59
	s_nop 0
	v_cndmask_b32_e64 v2, 0, 1, vcc
	v_cmp_ne_u32_e32 vcc, 0, v16
	v_cndmask_b32_e64 v17, v17, v16, s[8:9]
	v_readlane_b32 s8, v254, 12
	v_addc_co_u32_e32 v0, vcc, v0, v2, vcc
	v_max_u32_e32 v3, 1, v17
	v_max_u32_e32 v2, 1, v0
	v_mov_b32_e32 v0, s8
	v_readlane_b32 s8, v254, 13
	ds_write_b32 v0, v3
	s_nop 0
	v_mov_b32_e32 v0, s8
	ds_write_b32 v0, v2
.LBB0_1112:
	s_mov_b64 s[10:11], exec
	v_mbcnt_lo_u32_b32 v0, s10, 0
	v_mbcnt_hi_u32_b32 v0, s11, v0
	v_cmp_eq_u32_e32 vcc, 0, v0
	s_and_saveexec_b64 s[8:9], vcc
	s_cbranch_execz .LBB0_1114
	v_readlane_b32 s20, v255, 33
	s_cmp_lg_u32 s20, 0
	s_cbranch_scc1 .Lxb_flag
	s_bcnt1_i32_b64 s10, s[10:11]
	v_mov_b32_e32 v4, s10
	v_readlane_b32 s10, v253, 26
	v_readlane_b32 s11, v253, 27
	s_nop 4
	global_atomic_add v4, v1, v4, s[10:11] sc0
	s_branch .LBB0_1114
.Lxb_flag:
	v_readlane_b32 s21, v255, 32
	v_readfirstlane_b32 s28, v3
	v_readlane_b32 s10, v253, 26
	v_readlane_b32 s11, v253, 27
	s_add_u32 s10, s10, 0x8000
	s_addc_u32 s11, s11, 0
	s_add_i32 s22, s20, 1
	s_lshl_b32 s23, s21, 2
	v_mov_b32_e32 v4, s22
	v_mov_b32_e32 v5, s23
	s_mul_i32 s29, s20, s28
	s_nop 1
	global_store_dword v5, v4, s[10:11]
	s_cmp_lg_u32 s21, 0
	s_cbranch_scc1 .Lxb_set
	s_mov_b64 s[26:27], exec
	s_lshl_b64 s[30:31], 1, s28
	s_sub_u32 s30, s30, 1
	s_subb_u32 s31, s31, 0
	s_mov_b64 exec, s[30:31]
	v_mbcnt_lo_u32_b32 v6, -1, 0
	v_lshlrev_b32_e32 v6, 2, v6
.Lxb_poll:
	global_load_dword v5, v6, s[10:11] sc1
	s_waitcnt vmcnt(0)
	v_cmp_ne_u32_e32 vcc, s22, v5
	s_nop 1
	s_cmp_eq_u64 vcc, 0
	s_cbranch_scc1 .Lxb_all
	s_sleep 1
	s_branch .Lxb_poll
.Lxb_all:
	s_mov_b64 exec, s[26:27]
	s_add_i32 s29, s29, s28
	s_add_i32 s29, s29, -1
.Lxb_set:
	v_mov_b32_e32 v4, s29
.LBB0_1114:
	s_or_b64 exec, exec, s[8:9]
	v_cvt_f32_u32_e32 v5, v3
	s_waitcnt vmcnt(0)
	v_readfirstlane_b32 s8, v4
	v_readlane_b32 s20, v255, 33
	s_cmp_lg_u32 s20, 0
	s_cbranch_scc1 .Lxb_notfirst
	s_nop 3
	v_writelane_b32 v255, s8, 32
.Lxb_notfirst:
	s_add_i32 s20, s20, 1
	v_writelane_b32 v255, s20, 33
	v_sub_u32_e32 v4, 0, v3
	v_rcp_iflag_f32_e32 v5, v5
	v_add_u32_e32 v6, s8, v0
	v_mul_f32_e32 v5, 0x4f7ffffe, v5
	v_cvt_u32_f32_e32 v5, v5
	v_mul_lo_u32 v0, v4, v5
	v_mul_hi_u32 v0, v5, v0
	v_add_u32_e32 v0, v5, v0
	v_mul_hi_u32 v0, v6, v0
	v_mul_lo_u32 v4, v0, v3
	v_sub_u32_e32 v4, v6, v4
	v_add_u32_e32 v5, 1, v0
	v_cmp_ge_u32_e32 vcc, v4, v3
	s_nop 1
	v_cndmask_b32_e32 v0, v0, v5, vcc
	v_sub_u32_e32 v5, v4, v3
	v_cndmask_b32_e32 v4, v4, v5, vcc
	v_add_u32_e32 v5, 1, v0
	v_cmp_ge_u32_e32 vcc, v4, v3
	v_add_u32_e32 v4, 1, v6
	s_nop 0
	v_cndmask_b32_e32 v0, v0, v5, vcc
	v_add_u32_e32 v7, 1, v0
	v_mul_lo_u32 v5, v3, v0
	v_add_u32_e32 v3, v5, v3
	v_cmp_ne_u32_e32 vcc, v4, v3
	s_and_saveexec_b64 s[8:9], vcc
	s_xor_b64 s[8:9], exec, s[8:9]
	s_cbranch_execz .LBB0_1128
	v_readlane_b32 s10, v253, 28
	v_readlane_b32 s11, v253, 29
	s_waitcnt lgkmcnt(0)
	s_nop 3
	buffer_inv sc1
	global_load_dword v2, v1, s[10:11] sc1
	s_waitcnt vmcnt(0)
	v_cmp_eq_u32_e32 vcc, v2, v0
	s_and_saveexec_b64 s[10:11], vcc
	s_cbranch_execz .LBB0_1127
	s_mov_b32 s24, 1
	s_mov_b64 s[12:13], 0
	s_branch .LBB0_1118
